# prep pass fast path: chunks of 4 interior tokens share 19 pooling rows and 6 conv rows (35 loads instead of 92, no per-row address/mask arithmetic); boundary chunks keep hipcc's path
# speedup vs baseline: 1.0045x; 1.0025x over previous
; __device__ __forceinline__ void prep_tokens(const bf16* Y, bf16* MIX, const float* scw, int tb, int te, int wi, int ws_, int lane) {
;     int inp_ = INP; asm volatile("" : "+s"(inp_));
;     const int ch = 4 * lane, grp = lane >> 4, hw = 1 << grp;
;     const f32x4 cw0 = *(const f32x4*)(scw + ch), cw1 = *(const f32x4*)(scw + 256 + ch), cw2 = *(const f32x4*)(scw + 512 + ch);
;     for (int t0 = tb + wi * 4; t0 < te; t0 += ws_ * 4)
;     for (int ti = 0; ti < 4; ++ti) { const int t = t0 + ti;
;         const bf16* y = Y + (size_t)t * INP; const bool lat = t < TLAT; const int n = lat ? (t & (SEQ - 1)) : ((t - TLAT) & (CTXL - 1)); const int len = lat ? SEQ : CTXL;
;         const bool hp = n > 0, hn = n < len - 1; const long op = hp ? -(long)inp_ : 0, on = hn ? (long)inp_ : 0; const float fp = hp ? 1.f : 0.f, fn = hn ? 1.f : 0.f;
;         const v2u gb = *(const v2u*)(y + 704 + ch), c1 = *(const v2u*)(y + 960 + ch), i1 = *(const v2u*)(y + 1216 + ch);
;         const v2u c0 = *(const v2u*)(y + op + 960 + ch), i0 = *(const v2u*)(y + op + 1216 + ch), c2 = *(const v2u*)(y + on + 960 + ch), i2 = *(const v2u*)(y + on + 1216 + ch);
;         v2u pv[16]; float pw[16];
; #pragma unroll
;         for (int d = -8; d < 8; ++d) { const int s = n + d; const bool ok = d >= -hw && d < hw && s >= 0 && s < len; pw[d + 8] = ok ? 1.f : 0.f;
;             pv[d + 8] = *(const v2u*)(y + (ok ? (long)d * inp_ : 0) + 448 + ch); }
.LBB0_585:
	v_readlane_b32 s18, v253, 37
	v_readlane_b32 s20, v253, 39
	s_and_b64 vcc, exec, s[4:5]
	v_readlane_b32 s19, v253, 38
	v_readlane_b32 s21, v253, 40
	s_cbranch_vccz .LBB0_606
	v_mov_b32_e32 v12, v242
	v_readlane_b32 s1, v253, 14
	v_readfirstlane_b32 s0, v12
	s_ashr_i32 s0, s0, 6
	s_add_i32 s10, s1, s0
	s_movk_i32 s26, 0x600
	s_cmpk_gt_i32 s10, 0x1fff
	s_cbranch_scc1 .LBB0_606
	v_writelane_b32 v254, s54, 10
	v_writelane_b32 v254, s88, 11
	v_and_b32_e32 v13, 63, v12
	v_lshlrev_b32_e32 v8, 4, v13
	v_writelane_b32 v254, s89, 12
	v_writelane_b32 v254, s90, 13
	s_load_dwordx2 s[2:3], s[90:91], 0x98
	v_readlane_b32 s18, v253, 25
	v_writelane_b32 v254, s91, 14
	s_waitcnt lgkmcnt(0)
	s_mov_b64 s[38:39], s[30:31]
	v_readlane_b32 s1, v254, 5
	s_mul_i32 s4, s1, 0x300
	s_ashr_i32 s5, s4, 31
	s_lshl_b64 s[4:5], s[4:5], 2
	s_add_u32 s2, s2, s4
	s_addc_u32 s3, s3, s5
	global_load_dwordx4 v[0:3], v8, s[2:3] offset:2048
	global_load_dwordx4 v[4:7], v8, s[2:3]
	s_nop 0
	global_load_dwordx4 v[8:11], v8, s[2:3] offset:1024
	s_lshl_b32 s28, s10, 2
	s_ashr_i32 s27, s26, 31
	s_sub_u32 s2, 0, s26
	s_subb_u32 s52, 0, s27
	s_lshl_b64 s[12:13], s[26:27], 3
	s_sub_u32 s3, 0, s12
	s_subb_u32 s68, 0, s13
	s_lshl_b64 s[14:15], s[26:27], 2
	s_sub_u32 s40, 0, s14
	s_subb_u32 s33, 0, s15
	s_lshl_b64 s[16:17], s[26:27], 1
	s_sub_u32 s69, 0, s16
	s_subb_u32 s1, 0, s17
	s_lshl_b32 s0, s0, 2
	s_ashr_i32 s29, s28, 31
	s_add_i32 s0, s18, s0
	s_lshl_b64 s[18:19], s[28:29], 11
	s_add_u32 s30, s38, s18
	s_addc_u32 s31, s39, s19
	s_add_u32 s18, s38, 0xa200380
	s_mul_i32 s34, s26, 14
	s_addc_u32 s19, s39, 0
	s_mulk_i32 s10, 0x3000
	s_mul_hi_i32 s25, s26, 14
	s_mul_hi_i32 s29, s28, 0xc00
	s_add_u32 s34, s10, s34
	s_addc_u32 s25, s29, s25
	s_add_u32 s34, s18, s34
	s_mul_i32 s24, s26, 12
	s_addc_u32 s35, s19, s25
	s_mul_hi_i32 s23, s26, 12
	s_add_u32 s24, s10, s24
	s_addc_u32 s23, s29, s23
	s_add_u32 s36, s18, s24
	s_addc_u32 s37, s19, s23
	s_add_u32 s46, s38, s10
	s_mul_i32 s22, s26, 10
	s_addc_u32 s47, s39, s29
	s_mul_hi_i32 s21, s26, 10
	s_add_u32 s22, s10, s22
	s_addc_u32 s21, s29, s21
	s_add_u32 s48, s18, s22
	s_addc_u32 s49, s19, s21
	s_add_u32 s12, s10, s12
	s_addc_u32 s13, s29, s13
	s_add_u32 s50, s18, s12
	s_mul_i32 s20, s26, 6
	s_addc_u32 s51, s19, s13
	s_mul_hi_i32 s11, s26, 6
	s_add_u32 s12, s10, s20
	s_addc_u32 s11, s29, s11
	s_add_u32 s54, s18, s12
	s_addc_u32 s55, s19, s11
	s_add_u32 s11, s10, s16
	s_addc_u32 s12, s29, s17
	s_add_u32 s56, s18, s11
	s_addc_u32 s57, s19, s12
	s_add_u32 s10, s10, s14
	s_addc_u32 s11, s29, s15
	v_bfe_u32 v12, v12, 4, 2
	s_add_u32 s58, s18, s10
	v_lshlrev_b32_e64 v45, v12, 1
	v_cmp_eq_u32_e64 s[4:5], 3, v12
	v_cmp_lt_u32_e64 s[6:7], 31, v13
	v_cmp_lt_u32_e64 s[8:9], 15, v13
	v_lshlrev_b32_e32 v208, 3, v13
	s_addc_u32 s59, s19, s11
	v_add_u32_e32 v104, 0, v208
	v_add_u32_e32 v105, 6144, v208
	v_add_u32_e32 v106, 12288, v208
	v_add_u32_e32 v107, 18432, v208
	v_add_u32_e32 v108, 24576, v208
	v_add_u32_e32 v109, 30720, v208
	v_add_u32_e32 v110, 36864, v208
	v_add_u32_e32 v111, 43008, v208
	v_add_u32_e32 v112, 49152, v208
	v_add_u32_e32 v113, 55296, v208
	v_add_u32_e32 v114, 0, v208
	v_add_u32_e32 v115, 2048, v208
	v_add_u32_e32 v116, 4096, v208
	v_add_u32_e32 v117, 6144, v208
	v_cmp_le_u32_e64 vcc, 8, v45
	v_cmp_le_u32_e64 s[94:95], 7, v45
	v_cmp_le_u32_e64 s[96:97], 6, v45
	v_cmp_le_u32_e64 s[98:99], 5, v45
	s_nop 1
	v_cndmask_b32_e64 v118, 0, 1.0, vcc
	v_cndmask_b32_e64 v119, 0, 1.0, s[94:95]
	v_cndmask_b32_e64 v120, 0, 1.0, s[96:97]
	v_cndmask_b32_e64 v121, 0, 1.0, s[98:99]
	v_cmp_le_u32_e64 vcc, 4, v45
	v_cmp_le_u32_e64 s[94:95], 3, v45
	v_cmp_le_u32_e64 s[96:97], 2, v45
	v_cmp_le_u32_e64 s[98:99], 1, v45
	s_nop 1
	v_cndmask_b32_e64 v122, 0, 1.0, vcc
	v_cndmask_b32_e64 v123, 0, 1.0, s[94:95]
	v_cndmask_b32_e64 v124, 0, 1.0, s[96:97]
	v_cndmask_b32_e64 v125, 0, 1.0, s[98:99]
	v_cmp_le_u32_e64 vcc, 1, v45
	v_cmp_le_u32_e64 s[94:95], 2, v45
	v_cmp_le_u32_e64 s[96:97], 3, v45
	v_cmp_le_u32_e64 s[98:99], 4, v45
	s_nop 1
	v_cndmask_b32_e64 v126, 0, 1.0, vcc
	v_cndmask_b32_e64 v127, 0, 1.0, s[94:95]
	v_cndmask_b32_e64 v128, 0, 1.0, s[96:97]
	v_cndmask_b32_e64 v129, 0, 1.0, s[98:99]
	v_cmp_le_u32_e64 vcc, 5, v45
	v_cmp_le_u32_e64 s[94:95], 6, v45
	v_cmp_le_u32_e64 s[96:97], 7, v45
	v_cmp_le_u32_e64 s[98:99], 8, v45
	s_nop 1
	v_cndmask_b32_e64 v130, 0, 1.0, vcc
	v_cndmask_b32_e64 v131, 0, 1.0, s[94:95]
	v_cndmask_b32_e64 v132, 0, 1.0, s[96:97]
	v_cndmask_b32_e64 v133, 0, 1.0, s[98:99]
	v_not_b32_e32 v234, v12
	v_ldexp_f32 v134, 1.0, v234
	v_mov_b32_e32 v135, v134
	s_branch .LBB0_589

; __device__ __forceinline__ void prep_tokens(const bf16* Y, bf16* MIX, const float* scw, int tb, int te, int wi, int ws_, int lane) {
;     ...
;     for (int t0 = tb + wi * 4; t0 < te; t0 += ws_ * 4)
;     for (int ti = 0; ti < 4; ++ti) { const int t = t0 + ti;
;         const bf16* y = Y + (size_t)t * INP; const bool lat = t < TLAT; const int n = lat ? (t & (SEQ - 1)) : ((t - TLAT) & (CTXL - 1)); const int len = lat ? SEQ : CTXL;
;         const bool hp = n > 0, hn = n < len - 1; const long op = hp ? -(long)inp_ : 0, on = hn ? (long)inp_ : 0; const float fp = hp ? 1.f : 0.f, fn = hn ? 1.f : 0.f;
;         const v2u gb = *(const v2u*)(y + 704 + ch), c1 = *(const v2u*)(y + 960 + ch), i1 = *(const v2u*)(y + 1216 + ch);
;         const v2u c0 = *(const v2u*)(y + op + 960 + ch), i0 = *(const v2u*)(y + op + 1216 + ch), c2 = *(const v2u*)(y + on + 960 + ch), i2 = *(const v2u*)(y + on + 1216 + ch);
;         v2u pv[16]; float pw[16];
; #pragma unroll
;         for (int d = -8; d < 8; ++d) { const int s = n + d; const bool ok = d >= -hw && d < hw && s >= 0 && s < len; pw[d + 8] = ok ? 1.f : 0.f;
;             pv[d + 8] = *(const v2u*)(y + (ok ? (long)d * inp_ : 0) + 448 + ch); }
;         { const f32x4 w0 = cw0 * fp, w2 = cw2 * fn;
;           const float o0 = bflo(gb.x) * (w0.x * bflo(c0.x) * bflo(i0.x) + cw1.x * bflo(c1.x) * bflo(i1.x) + w2.x * bflo(c2.x) * bflo(i2.x));
;           const float o1 = bfhi(gb.x) * (w0.y * bfhi(c0.x) * bfhi(i0.x) + cw1.y * bfhi(c1.x) * bfhi(i1.x) + w2.y * bfhi(c2.x) * bfhi(i2.x));
;           const float o2 = bflo(gb.y) * (w0.z * bflo(c0.y) * bflo(i0.y) + cw1.z * bflo(c1.y) * bflo(i1.y) + w2.z * bflo(c2.y) * bflo(i2.y));
;           const float o3 = bfhi(gb.y) * (w0.w * bfhi(c0.y) * bfhi(i0.y) + cw1.w * bfhi(c1.y) * bfhi(i1.y) + w2.w * bfhi(c2.y) * bfhi(i2.y));
;           v2u w; w.x = pk2(o0, o1); w.y = pk2(o2, o3); *(v2u*)(MIX + (size_t)t * DM + 768 + ch) = w; }
;         { float s0 = 0.f, s1 = 0.f, s2 = 0.f, s3 = 0.f;
; #pragma unroll
;           for (int j = 0; j < 16; ++j) { s0 += pw[j] * bflo(pv[j].x); s1 += pw[j] * bfhi(pv[j].x); s2 += pw[j] * bflo(pv[j].y); s3 += pw[j] * bfhi(pv[j].y); }
.LBB0_589:
	s_and_b32 s10, s28, 0x1fff
	s_sub_u32 s10, s10, 8
	s_cmp_le_u32 s10, 8172
	s_cbranch_scc0 .Lprep_slow
	s_add_u32 s10, s46, 0xa1fa000
	s_addc_u32 s11, s47, 0
	s_add_u32 s12, s30, 0x19800000
	s_addc_u32 s13, s31, 0
	global_load_dwordx2 v[136:137], v104, s[10:11] offset:896
	global_load_dwordx2 v[138:139], v105, s[10:11] offset:-2176
	global_load_dwordx2 v[140:141], v105, s[10:11] offset:896
	global_load_dwordx2 v[142:143], v106, s[10:11] offset:-2176
	global_load_dwordx2 v[144:145], v106, s[10:11] offset:896
	global_load_dwordx2 v[146:147], v107, s[10:11] offset:-2176
	global_load_dwordx2 v[148:149], v107, s[10:11] offset:896
	global_load_dwordx2 v[150:151], v108, s[10:11] offset:-2176
	global_load_dwordx2 v[152:153], v108, s[10:11] offset:896
	global_load_dwordx2 v[154:155], v109, s[10:11] offset:-2176
	global_load_dwordx2 v[156:157], v109, s[10:11] offset:896
	global_load_dwordx2 v[158:159], v110, s[10:11] offset:-2176
	global_load_dwordx2 v[160:161], v110, s[10:11] offset:896
	global_load_dwordx2 v[162:163], v111, s[10:11] offset:-2176
	global_load_dwordx2 v[164:165], v111, s[10:11] offset:896
	global_load_dwordx2 v[166:167], v112, s[10:11] offset:-2176
	global_load_dwordx2 v[168:169], v112, s[10:11] offset:896
	global_load_dwordx2 v[170:171], v113, s[10:11] offset:-2176
	global_load_dwordx2 v[172:173], v113, s[10:11] offset:896
	global_load_dwordx2 v[174:175], v108, s[10:11] offset:-1152
	global_load_dwordx2 v[186:187], v108, s[10:11] offset:-640
	global_load_dwordx2 v[176:177], v108, s[10:11] offset:1920
	global_load_dwordx2 v[188:189], v108, s[10:11] offset:2432
	global_load_dwordx2 v[178:179], v109, s[10:11] offset:-1152
	global_load_dwordx2 v[190:191], v109, s[10:11] offset:-640
	global_load_dwordx2 v[180:181], v109, s[10:11] offset:1920
	global_load_dwordx2 v[192:193], v109, s[10:11] offset:2432
	global_load_dwordx2 v[182:183], v110, s[10:11] offset:-1152
	global_load_dwordx2 v[194:195], v110, s[10:11] offset:-640
	global_load_dwordx2 v[184:185], v110, s[10:11] offset:1920
	global_load_dwordx2 v[196:197], v110, s[10:11] offset:2432
	global_load_dwordx2 v[198:199], v108, s[10:11] offset:1408
	global_load_dwordx2 v[200:201], v109, s[10:11] offset:-1664
	global_load_dwordx2 v[202:203], v109, s[10:11] offset:1408
	global_load_dwordx2 v[204:205], v110, s[10:11] offset:-1664
	s_waitcnt vmcnt(34)
	v_lshlrev_b32_e32 v226, 16, v136
	v_and_b32_e32 v227, 0xffff0000, v136
	v_lshlrev_b32_e32 v228, 16, v137
	v_and_b32_e32 v229, 0xffff0000, v137
	v_pk_fma_f32 v[210:211], v[226:227], v[118:119], 0 op_sel_hi:[1,0,1]
	v_pk_fma_f32 v[212:213], v[228:229], v[118:119], 0 op_sel_hi:[1,0,1]
	s_waitcnt vmcnt(33)
	v_lshlrev_b32_e32 v230, 16, v138
	v_and_b32_e32 v231, 0xffff0000, v138
	v_lshlrev_b32_e32 v232, 16, v139
	v_and_b32_e32 v233, 0xffff0000, v139
	v_pk_fma_f32 v[210:211], v[230:231], v[118:119], v[210:211] op_sel:[0,1,0] op_sel_hi:[1,1,1]
	v_pk_fma_f32 v[212:213], v[232:233], v[118:119], v[212:213] op_sel:[0,1,0] op_sel_hi:[1,1,1]
	v_pk_fma_f32 v[214:215], v[230:231], v[118:119], 0 op_sel_hi:[1,0,1]
	v_pk_fma_f32 v[216:217], v[232:233], v[118:119], 0 op_sel_hi:[1,0,1]
	s_waitcnt vmcnt(32)
	v_lshlrev_b32_e32 v226, 16, v140
	v_and_b32_e32 v227, 0xffff0000, v140
	v_lshlrev_b32_e32 v228, 16, v141
	v_and_b32_e32 v229, 0xffff0000, v141
	v_pk_fma_f32 v[210:211], v[226:227], v[120:121], v[210:211] op_sel_hi:[1,0,1]
	v_pk_fma_f32 v[212:213], v[228:229], v[120:121], v[212:213] op_sel_hi:[1,0,1]
	v_pk_fma_f32 v[214:215], v[226:227], v[118:119], v[214:215] op_sel:[0,1,0] op_sel_hi:[1,1,1]
	v_pk_fma_f32 v[216:217], v[228:229], v[118:119], v[216:217] op_sel:[0,1,0] op_sel_hi:[1,1,1]
	v_pk_fma_f32 v[218:219], v[226:227], v[118:119], 0 op_sel_hi:[1,0,1]
	v_pk_fma_f32 v[220:221], v[228:229], v[118:119], 0 op_sel_hi:[1,0,1]
	s_waitcnt vmcnt(31)
	v_lshlrev_b32_e32 v230, 16, v142
	v_and_b32_e32 v231, 0xffff0000, v142
	v_lshlrev_b32_e32 v232, 16, v143
	v_and_b32_e32 v233, 0xffff0000, v143
	v_pk_fma_f32 v[210:211], v[230:231], v[120:121], v[210:211] op_sel:[0,1,0] op_sel_hi:[1,1,1]
	v_pk_fma_f32 v[212:213], v[232:233], v[120:121], v[212:213] op_sel:[0,1,0] op_sel_hi:[1,1,1]
	v_pk_fma_f32 v[214:215], v[230:231], v[120:121], v[214:215] op_sel_hi:[1,0,1]
	v_pk_fma_f32 v[216:217], v[232:233], v[120:121], v[216:217] op_sel_hi:[1,0,1]
	v_pk_fma_f32 v[218:219], v[230:231], v[118:119], v[218:219] op_sel:[0,1,0] op_sel_hi:[1,1,1]
	v_pk_fma_f32 v[220:221], v[232:233], v[118:119], v[220:221] op_sel:[0,1,0] op_sel_hi:[1,1,1]
	v_pk_fma_f32 v[222:223], v[230:231], v[118:119], 0 op_sel_hi:[1,0,1]
	v_pk_fma_f32 v[224:225], v[232:233], v[118:119], 0 op_sel_hi:[1,0,1]
	s_waitcnt vmcnt(30)
	v_lshlrev_b32_e32 v226, 16, v144
	v_and_b32_e32 v227, 0xffff0000, v144
	v_lshlrev_b32_e32 v228, 16, v145
	v_and_b32_e32 v229, 0xffff0000, v145
	v_pk_fma_f32 v[210:211], v[226:227], v[122:123], v[210:211] op_sel_hi:[1,0,1]
	v_pk_fma_f32 v[212:213], v[228:229], v[122:123], v[212:213] op_sel_hi:[1,0,1]
	v_pk_fma_f32 v[214:215], v[226:227], v[120:121], v[214:215] op_sel:[0,1,0] op_sel_hi:[1,1,1]
	v_pk_fma_f32 v[216:217], v[228:229], v[120:121], v[216:217] op_sel:[0,1,0] op_sel_hi:[1,1,1]
	v_pk_fma_f32 v[218:219], v[226:227], v[120:121], v[218:219] op_sel_hi:[1,0,1]
	v_pk_fma_f32 v[220:221], v[228:229], v[120:121], v[220:221] op_sel_hi:[1,0,1]
	v_pk_fma_f32 v[222:223], v[226:227], v[118:119], v[222:223] op_sel:[0,1,0] op_sel_hi:[1,1,1]
	v_pk_fma_f32 v[224:225], v[228:229], v[118:119], v[224:225] op_sel:[0,1,0] op_sel_hi:[1,1,1]
	s_waitcnt vmcnt(29)
; __device__ __forceinline__ void prep_tokens(const bf16* Y, bf16* MIX, const float* scw, int tb, int te, int wi, int ws_, int lane) {
;     ...
;         { float s0 = 0.f, s1 = 0.f, s2 = 0.f, s3 = 0.f;
; #pragma unroll
;           for (int j = 0; j < 16; ++j) { s0 += pw[j] * bflo(pv[j].x); s1 += pw[j] * bfhi(pv[j].x); s2 += pw[j] * bflo(pv[j].y); s3 += pw[j] * bfhi(pv[j].y); }
	v_lshlrev_b32_e32 v230, 16, v146
	v_and_b32_e32 v231, 0xffff0000, v146
	v_lshlrev_b32_e32 v232, 16, v147
	v_and_b32_e32 v233, 0xffff0000, v147
	v_pk_fma_f32 v[210:211], v[230:231], v[122:123], v[210:211] op_sel:[0,1,0] op_sel_hi:[1,1,1]
	v_pk_fma_f32 v[212:213], v[232:233], v[122:123], v[212:213] op_sel:[0,1,0] op_sel_hi:[1,1,1]
	v_pk_fma_f32 v[214:215], v[230:231], v[122:123], v[214:215] op_sel_hi:[1,0,1]
	v_pk_fma_f32 v[216:217], v[232:233], v[122:123], v[216:217] op_sel_hi:[1,0,1]
	v_pk_fma_f32 v[218:219], v[230:231], v[120:121], v[218:219] op_sel:[0,1,0] op_sel_hi:[1,1,1]
	v_pk_fma_f32 v[220:221], v[232:233], v[120:121], v[220:221] op_sel:[0,1,0] op_sel_hi:[1,1,1]
	v_pk_fma_f32 v[222:223], v[230:231], v[120:121], v[222:223] op_sel_hi:[1,0,1]
	v_pk_fma_f32 v[224:225], v[232:233], v[120:121], v[224:225] op_sel_hi:[1,0,1]
	s_waitcnt vmcnt(28)
	v_lshlrev_b32_e32 v226, 16, v148
	v_and_b32_e32 v227, 0xffff0000, v148
	v_lshlrev_b32_e32 v228, 16, v149
	v_and_b32_e32 v229, 0xffff0000, v149
	v_pk_fma_f32 v[210:211], v[226:227], v[124:125], v[210:211] op_sel_hi:[1,0,1]
	v_pk_fma_f32 v[212:213], v[228:229], v[124:125], v[212:213] op_sel_hi:[1,0,1]
	v_pk_fma_f32 v[214:215], v[226:227], v[122:123], v[214:215] op_sel:[0,1,0] op_sel_hi:[1,1,1]
	v_pk_fma_f32 v[216:217], v[228:229], v[122:123], v[216:217] op_sel:[0,1,0] op_sel_hi:[1,1,1]
	v_pk_fma_f32 v[218:219], v[226:227], v[122:123], v[218:219] op_sel_hi:[1,0,1]
	v_pk_fma_f32 v[220:221], v[228:229], v[122:123], v[220:221] op_sel_hi:[1,0,1]
	v_pk_fma_f32 v[222:223], v[226:227], v[120:121], v[222:223] op_sel:[0,1,0] op_sel_hi:[1,1,1]
	v_pk_fma_f32 v[224:225], v[228:229], v[120:121], v[224:225] op_sel:[0,1,0] op_sel_hi:[1,1,1]
	s_waitcnt vmcnt(27)
	v_lshlrev_b32_e32 v230, 16, v150
	v_and_b32_e32 v231, 0xffff0000, v150
	v_lshlrev_b32_e32 v232, 16, v151
	v_and_b32_e32 v233, 0xffff0000, v151
	v_pk_fma_f32 v[210:211], v[230:231], v[124:125], v[210:211] op_sel:[0,1,0] op_sel_hi:[1,1,1]
	v_pk_fma_f32 v[212:213], v[232:233], v[124:125], v[212:213] op_sel:[0,1,0] op_sel_hi:[1,1,1]
	v_pk_fma_f32 v[214:215], v[230:231], v[124:125], v[214:215] op_sel_hi:[1,0,1]
	v_pk_fma_f32 v[216:217], v[232:233], v[124:125], v[216:217] op_sel_hi:[1,0,1]
	v_pk_fma_f32 v[218:219], v[230:231], v[122:123], v[218:219] op_sel:[0,1,0] op_sel_hi:[1,1,1]
	v_pk_fma_f32 v[220:221], v[232:233], v[122:123], v[220:221] op_sel:[0,1,0] op_sel_hi:[1,1,1]
	v_pk_fma_f32 v[222:223], v[230:231], v[122:123], v[222:223] op_sel_hi:[1,0,1]
	v_pk_fma_f32 v[224:225], v[232:233], v[122:123], v[224:225] op_sel_hi:[1,0,1]
	s_waitcnt vmcnt(26)
	v_lshlrev_b32_e32 v226, 16, v152
	v_and_b32_e32 v227, 0xffff0000, v152
	v_lshlrev_b32_e32 v228, 16, v153
	v_and_b32_e32 v229, 0xffff0000, v153
	v_pk_fma_f32 v[210:211], v[226:227], v[126:127], v[210:211] op_sel_hi:[1,0,1]
	v_pk_fma_f32 v[212:213], v[228:229], v[126:127], v[212:213] op_sel_hi:[1,0,1]
	v_pk_fma_f32 v[214:215], v[226:227], v[124:125], v[214:215] op_sel:[0,1,0] op_sel_hi:[1,1,1]
	v_pk_fma_f32 v[216:217], v[228:229], v[124:125], v[216:217] op_sel:[0,1,0] op_sel_hi:[1,1,1]
	v_pk_fma_f32 v[218:219], v[226:227], v[124:125], v[218:219] op_sel_hi:[1,0,1]
	v_pk_fma_f32 v[220:221], v[228:229], v[124:125], v[220:221] op_sel_hi:[1,0,1]
	v_pk_fma_f32 v[222:223], v[226:227], v[122:123], v[222:223] op_sel:[0,1,0] op_sel_hi:[1,1,1]
	v_pk_fma_f32 v[224:225], v[228:229], v[122:123], v[224:225] op_sel:[0,1,0] op_sel_hi:[1,1,1]
	s_waitcnt vmcnt(25)
	v_lshlrev_b32_e32 v230, 16, v154
	v_and_b32_e32 v231, 0xffff0000, v154
	v_lshlrev_b32_e32 v232, 16, v155
	v_and_b32_e32 v233, 0xffff0000, v155
	v_pk_fma_f32 v[210:211], v[230:231], v[126:127], v[210:211] op_sel:[0,1,0] op_sel_hi:[1,1,1]
	v_pk_fma_f32 v[212:213], v[232:233], v[126:127], v[212:213] op_sel:[0,1,0] op_sel_hi:[1,1,1]
	v_pk_fma_f32 v[214:215], v[230:231], v[126:127], v[214:215] op_sel_hi:[1,0,1]
	v_pk_fma_f32 v[216:217], v[232:233], v[126:127], v[216:217] op_sel_hi:[1,0,1]
	v_pk_fma_f32 v[218:219], v[230:231], v[124:125], v[218:219] op_sel:[0,1,0] op_sel_hi:[1,1,1]
	v_pk_fma_f32 v[220:221], v[232:233], v[124:125], v[220:221] op_sel:[0,1,0] op_sel_hi:[1,1,1]
	v_pk_fma_f32 v[222:223], v[230:231], v[124:125], v[222:223] op_sel_hi:[1,0,1]
	v_pk_fma_f32 v[224:225], v[232:233], v[124:125], v[224:225] op_sel_hi:[1,0,1]
	s_waitcnt vmcnt(24)
	v_lshlrev_b32_e32 v226, 16, v156
	v_and_b32_e32 v227, 0xffff0000, v156
	v_lshlrev_b32_e32 v228, 16, v157
	v_and_b32_e32 v229, 0xffff0000, v157
	v_pk_fma_f32 v[210:211], v[226:227], v[128:129], v[210:211] op_sel_hi:[1,0,1]
	v_pk_fma_f32 v[212:213], v[228:229], v[128:129], v[212:213] op_sel_hi:[1,0,1]
	v_pk_fma_f32 v[214:215], v[226:227], v[126:127], v[214:215] op_sel:[0,1,0] op_sel_hi:[1,1,1]
	v_pk_fma_f32 v[216:217], v[228:229], v[126:127], v[216:217] op_sel:[0,1,0] op_sel_hi:[1,1,1]
	v_pk_fma_f32 v[218:219], v[226:227], v[126:127], v[218:219] op_sel_hi:[1,0,1]
	v_pk_fma_f32 v[220:221], v[228:229], v[126:127], v[220:221] op_sel_hi:[1,0,1]
	v_pk_fma_f32 v[222:223], v[226:227], v[124:125], v[222:223] op_sel:[0,1,0] op_sel_hi:[1,1,1]
	v_pk_fma_f32 v[224:225], v[228:229], v[124:125], v[224:225] op_sel:[0,1,0] op_sel_hi:[1,1,1]
	s_waitcnt vmcnt(23)
	v_lshlrev_b32_e32 v230, 16, v158
	v_and_b32_e32 v231, 0xffff0000, v158
	v_lshlrev_b32_e32 v232, 16, v159
	v_and_b32_e32 v233, 0xffff0000, v159
	v_pk_fma_f32 v[210:211], v[230:231], v[128:129], v[210:211] op_sel:[0,1,0] op_sel_hi:[1,1,1]
	v_pk_fma_f32 v[212:213], v[232:233], v[128:129], v[212:213] op_sel:[0,1,0] op_sel_hi:[1,1,1]
	v_pk_fma_f32 v[214:215], v[230:231], v[128:129], v[214:215] op_sel_hi:[1,0,1]
	v_pk_fma_f32 v[216:217], v[232:233], v[128:129], v[216:217] op_sel_hi:[1,0,1]
	v_pk_fma_f32 v[218:219], v[230:231], v[126:127], v[218:219] op_sel:[0,1,0] op_sel_hi:[1,1,1]
	v_pk_fma_f32 v[220:221], v[232:233], v[126:127], v[220:221] op_sel:[0,1,0] op_sel_hi:[1,1,1]
	v_pk_fma_f32 v[222:223], v[230:231], v[126:127], v[222:223] op_sel_hi:[1,0,1]
	v_pk_fma_f32 v[224:225], v[232:233], v[126:127], v[224:225] op_sel_hi:[1,0,1]
	s_waitcnt vmcnt(22)
; __device__ __forceinline__ void prep_tokens(const bf16* Y, bf16* MIX, const float* scw, int tb, int te, int wi, int ws_, int lane) {
;     ...
;         { float s0 = 0.f, s1 = 0.f, s2 = 0.f, s3 = 0.f;
; #pragma unroll
;           for (int j = 0; j < 16; ++j) { s0 += pw[j] * bflo(pv[j].x); s1 += pw[j] * bfhi(pv[j].x); s2 += pw[j] * bflo(pv[j].y); s3 += pw[j] * bfhi(pv[j].y); }
	v_lshlrev_b32_e32 v226, 16, v160
	v_and_b32_e32 v227, 0xffff0000, v160
	v_lshlrev_b32_e32 v228, 16, v161
	v_and_b32_e32 v229, 0xffff0000, v161
	v_pk_fma_f32 v[210:211], v[226:227], v[130:131], v[210:211] op_sel_hi:[1,0,1]
	v_pk_fma_f32 v[212:213], v[228:229], v[130:131], v[212:213] op_sel_hi:[1,0,1]
	v_pk_fma_f32 v[214:215], v[226:227], v[128:129], v[214:215] op_sel:[0,1,0] op_sel_hi:[1,1,1]
	v_pk_fma_f32 v[216:217], v[228:229], v[128:129], v[216:217] op_sel:[0,1,0] op_sel_hi:[1,1,1]
	v_pk_fma_f32 v[218:219], v[226:227], v[128:129], v[218:219] op_sel_hi:[1,0,1]
	v_pk_fma_f32 v[220:221], v[228:229], v[128:129], v[220:221] op_sel_hi:[1,0,1]
	v_pk_fma_f32 v[222:223], v[226:227], v[126:127], v[222:223] op_sel:[0,1,0] op_sel_hi:[1,1,1]
	v_pk_fma_f32 v[224:225], v[228:229], v[126:127], v[224:225] op_sel:[0,1,0] op_sel_hi:[1,1,1]
	s_waitcnt vmcnt(21)
	v_lshlrev_b32_e32 v230, 16, v162
	v_and_b32_e32 v231, 0xffff0000, v162
	v_lshlrev_b32_e32 v232, 16, v163
	v_and_b32_e32 v233, 0xffff0000, v163
	v_pk_fma_f32 v[210:211], v[230:231], v[130:131], v[210:211] op_sel:[0,1,0] op_sel_hi:[1,1,1]
	v_pk_fma_f32 v[212:213], v[232:233], v[130:131], v[212:213] op_sel:[0,1,0] op_sel_hi:[1,1,1]
	v_pk_fma_f32 v[214:215], v[230:231], v[130:131], v[214:215] op_sel_hi:[1,0,1]
	v_pk_fma_f32 v[216:217], v[232:233], v[130:131], v[216:217] op_sel_hi:[1,0,1]
	v_pk_fma_f32 v[218:219], v[230:231], v[128:129], v[218:219] op_sel:[0,1,0] op_sel_hi:[1,1,1]
	v_pk_fma_f32 v[220:221], v[232:233], v[128:129], v[220:221] op_sel:[0,1,0] op_sel_hi:[1,1,1]
	v_pk_fma_f32 v[222:223], v[230:231], v[128:129], v[222:223] op_sel_hi:[1,0,1]
	v_pk_fma_f32 v[224:225], v[232:233], v[128:129], v[224:225] op_sel_hi:[1,0,1]
	s_waitcnt vmcnt(20)
	v_lshlrev_b32_e32 v226, 16, v164
	v_and_b32_e32 v227, 0xffff0000, v164
	v_lshlrev_b32_e32 v228, 16, v165
	v_and_b32_e32 v229, 0xffff0000, v165
	v_pk_fma_f32 v[210:211], v[226:227], v[132:133], v[210:211] op_sel_hi:[1,0,1]
	v_pk_fma_f32 v[212:213], v[228:229], v[132:133], v[212:213] op_sel_hi:[1,0,1]
	v_pk_fma_f32 v[214:215], v[226:227], v[130:131], v[214:215] op_sel:[0,1,0] op_sel_hi:[1,1,1]
	v_pk_fma_f32 v[216:217], v[228:229], v[130:131], v[216:217] op_sel:[0,1,0] op_sel_hi:[1,1,1]
	v_pk_fma_f32 v[218:219], v[226:227], v[130:131], v[218:219] op_sel_hi:[1,0,1]
	v_pk_fma_f32 v[220:221], v[228:229], v[130:131], v[220:221] op_sel_hi:[1,0,1]
	v_pk_fma_f32 v[222:223], v[226:227], v[128:129], v[222:223] op_sel:[0,1,0] op_sel_hi:[1,1,1]
	v_pk_fma_f32 v[224:225], v[228:229], v[128:129], v[224:225] op_sel:[0,1,0] op_sel_hi:[1,1,1]
	s_waitcnt vmcnt(19)
	v_lshlrev_b32_e32 v230, 16, v166
	v_and_b32_e32 v231, 0xffff0000, v166
	v_lshlrev_b32_e32 v232, 16, v167
	v_and_b32_e32 v233, 0xffff0000, v167
	v_pk_fma_f32 v[210:211], v[230:231], v[132:133], v[210:211] op_sel:[0,1,0] op_sel_hi:[1,1,1]
	v_pk_fma_f32 v[212:213], v[232:233], v[132:133], v[212:213] op_sel:[0,1,0] op_sel_hi:[1,1,1]
	v_pk_fma_f32 v[214:215], v[230:231], v[132:133], v[214:215] op_sel_hi:[1,0,1]
	v_pk_fma_f32 v[216:217], v[232:233], v[132:133], v[216:217] op_sel_hi:[1,0,1]
	v_pk_fma_f32 v[218:219], v[230:231], v[130:131], v[218:219] op_sel:[0,1,0] op_sel_hi:[1,1,1]
	v_pk_fma_f32 v[220:221], v[232:233], v[130:131], v[220:221] op_sel:[0,1,0] op_sel_hi:[1,1,1]
	v_pk_fma_f32 v[222:223], v[230:231], v[130:131], v[222:223] op_sel_hi:[1,0,1]
	v_pk_fma_f32 v[224:225], v[232:233], v[130:131], v[224:225] op_sel_hi:[1,0,1]
	s_waitcnt vmcnt(18)
	v_lshlrev_b32_e32 v226, 16, v168
	v_and_b32_e32 v227, 0xffff0000, v168
	v_lshlrev_b32_e32 v228, 16, v169
	v_and_b32_e32 v229, 0xffff0000, v169
	v_pk_fma_f32 v[214:215], v[226:227], v[132:133], v[214:215] op_sel:[0,1,0] op_sel_hi:[1,1,1]
	v_pk_fma_f32 v[216:217], v[228:229], v[132:133], v[216:217] op_sel:[0,1,0] op_sel_hi:[1,1,1]
	v_pk_fma_f32 v[218:219], v[226:227], v[132:133], v[218:219] op_sel_hi:[1,0,1]
	v_pk_fma_f32 v[220:221], v[228:229], v[132:133], v[220:221] op_sel_hi:[1,0,1]
	v_pk_fma_f32 v[222:223], v[226:227], v[130:131], v[222:223] op_sel:[0,1,0] op_sel_hi:[1,1,1]
	v_pk_fma_f32 v[224:225], v[228:229], v[130:131], v[224:225] op_sel:[0,1,0] op_sel_hi:[1,1,1]
	s_waitcnt vmcnt(17)
	v_lshlrev_b32_e32 v230, 16, v170
	v_and_b32_e32 v231, 0xffff0000, v170
	v_lshlrev_b32_e32 v232, 16, v171
	v_and_b32_e32 v233, 0xffff0000, v171
	v_pk_fma_f32 v[218:219], v[230:231], v[132:133], v[218:219] op_sel:[0,1,0] op_sel_hi:[1,1,1]
	v_pk_fma_f32 v[220:221], v[232:233], v[132:133], v[220:221] op_sel:[0,1,0] op_sel_hi:[1,1,1]
	v_pk_fma_f32 v[222:223], v[230:231], v[132:133], v[222:223] op_sel_hi:[1,0,1]
	v_pk_fma_f32 v[224:225], v[232:233], v[132:133], v[224:225] op_sel_hi:[1,0,1]
	s_waitcnt vmcnt(16)
; __device__ __forceinline__ void prep_tokens(const bf16* Y, bf16* MIX, const float* scw, int tb, int te, int wi, int ws_, int lane) {
;     ...
;         { const f32x4 w0 = cw0 * fp, w2 = cw2 * fn;
;           const float o0 = bflo(gb.x) * (w0.x * bflo(c0.x) * bflo(i0.x) + cw1.x * bflo(c1.x) * bflo(i1.x) + w2.x * bflo(c2.x) * bflo(i2.x));
;           const float o1 = bfhi(gb.x) * (w0.y * bfhi(c0.x) * bfhi(i0.x) + cw1.y * bfhi(c1.x) * bfhi(i1.x) + w2.y * bfhi(c2.x) * bfhi(i2.x));
;           const float o2 = bflo(gb.y) * (w0.z * bflo(c0.y) * bflo(i0.y) + cw1.z * bflo(c1.y) * bflo(i1.y) + w2.z * bflo(c2.y) * bflo(i2.y));
;           const float o3 = bfhi(gb.y) * (w0.w * bfhi(c0.y) * bfhi(i0.y) + cw1.w * bfhi(c1.y) * bfhi(i1.y) + w2.w * bfhi(c2.y) * bfhi(i2.y));
;           v2u w; w.x = pk2(o0, o1); w.y = pk2(o2, o3); *(v2u*)(MIX + (size_t)t * DM + 768 + ch) = w; }
;         { float s0 = 0.f, s1 = 0.f, s2 = 0.f, s3 = 0.f;
; #pragma unroll
;           for (int j = 0; j < 16; ++j) { s0 += pw[j] * bflo(pv[j].x); s1 += pw[j] * bfhi(pv[j].x); s2 += pw[j] * bflo(pv[j].y); s3 += pw[j] * bfhi(pv[j].y); }
;           const int lo = (n - hw) > 0 ? (n - hw) : 0, hi = (n + hw) < len ? (n + hw) : len; const float icnt = 1.0f / (float)(hi - lo);
;           const v2u pc = pv[8];
;           v2u w; w.x = pk2(s0 * icnt - bflo(pc.x), s1 * icnt - bfhi(pc.x)); w.y = pk2(s2 * icnt - bflo(pc.y), s3 * icnt - bfhi(pc.y)); *(v2u*)(MIX + (size_t)t * DM + 512 + ch) = w; }
	v_lshlrev_b32_e32 v226, 16, v172
	v_and_b32_e32 v227, 0xffff0000, v172
	v_lshlrev_b32_e32 v228, 16, v173
	v_and_b32_e32 v229, 0xffff0000, v173
	v_pk_fma_f32 v[222:223], v[226:227], v[132:133], v[222:223] op_sel:[0,1,0] op_sel_hi:[1,1,1]
	v_pk_fma_f32 v[224:225], v[228:229], v[132:133], v[224:225] op_sel:[0,1,0] op_sel_hi:[1,1,1]
	v_lshlrev_b32_e32 v226, 16, v152
	v_and_b32_e32 v227, 0xffff0000, v152
	v_lshlrev_b32_e32 v228, 16, v153
	v_and_b32_e32 v229, 0xffff0000, v153
	v_pk_fma_f32 v[210:211], v[210:211], v[134:135], v[226:227] op_sel_hi:[1,0,1] neg_lo:[0,0,1] neg_hi:[0,0,1]
	v_pk_fma_f32 v[212:213], v[212:213], v[134:135], v[228:229] op_sel_hi:[1,0,1] neg_lo:[0,0,1] neg_hi:[0,0,1]
	v_cvt_pk_bf16_f32 v234, v210, v211
	v_cvt_pk_bf16_f32 v235, v212, v213
	v_lshlrev_b32_e32 v226, 16, v154
	v_and_b32_e32 v227, 0xffff0000, v154
	v_lshlrev_b32_e32 v228, 16, v155
	v_and_b32_e32 v229, 0xffff0000, v155
	v_pk_fma_f32 v[214:215], v[214:215], v[134:135], v[226:227] op_sel_hi:[1,0,1] neg_lo:[0,0,1] neg_hi:[0,0,1]
	v_pk_fma_f32 v[216:217], v[216:217], v[134:135], v[228:229] op_sel_hi:[1,0,1] neg_lo:[0,0,1] neg_hi:[0,0,1]
	v_cvt_pk_bf16_f32 v236, v214, v215
	v_cvt_pk_bf16_f32 v237, v216, v217
	v_lshlrev_b32_e32 v226, 16, v156
	v_and_b32_e32 v227, 0xffff0000, v156
	v_lshlrev_b32_e32 v228, 16, v157
	v_and_b32_e32 v229, 0xffff0000, v157
	v_pk_fma_f32 v[218:219], v[218:219], v[134:135], v[226:227] op_sel_hi:[1,0,1] neg_lo:[0,0,1] neg_hi:[0,0,1]
	v_pk_fma_f32 v[220:221], v[220:221], v[134:135], v[228:229] op_sel_hi:[1,0,1] neg_lo:[0,0,1] neg_hi:[0,0,1]
	v_cvt_pk_bf16_f32 v238, v218, v219
	v_cvt_pk_bf16_f32 v239, v220, v221
	v_lshlrev_b32_e32 v226, 16, v158
	v_and_b32_e32 v227, 0xffff0000, v158
	v_lshlrev_b32_e32 v228, 16, v159
	v_and_b32_e32 v229, 0xffff0000, v159
	v_pk_fma_f32 v[222:223], v[222:223], v[134:135], v[226:227] op_sel_hi:[1,0,1] neg_lo:[0,0,1] neg_hi:[0,0,1]
	v_pk_fma_f32 v[224:225], v[224:225], v[134:135], v[228:229] op_sel_hi:[1,0,1] neg_lo:[0,0,1] neg_hi:[0,0,1]
	v_cvt_pk_bf16_f32 v240, v222, v223
	v_cvt_pk_bf16_f32 v241, v224, v225
	global_store_dwordx2 v114, v[234:235], s[12:13] offset:1024
	global_store_dwordx2 v115, v[236:237], s[12:13] offset:1024
	global_store_dwordx2 v116, v[238:239], s[12:13] offset:1024
	global_store_dwordx2 v117, v[240:241], s[12:13] offset:1024
	s_waitcnt vmcnt(10)
	s_waitcnt vmcnt(3)
	v_lshlrev_b32_e32 v226, 16, v174
	v_and_b32_e32 v227, 0xffff0000, v174
	v_lshlrev_b32_e32 v228, 16, v175
	v_and_b32_e32 v229, 0xffff0000, v175
	v_lshlrev_b32_e32 v230, 16, v186
	v_and_b32_e32 v231, 0xffff0000, v186
	v_lshlrev_b32_e32 v232, 16, v187
	v_and_b32_e32 v233, 0xffff0000, v187
	v_pk_mul_f32 v[214:215], v[4:5], v[226:227]
	v_pk_mul_f32 v[210:211], v[214:215], v[230:231]
	v_pk_mul_f32 v[216:217], v[6:7], v[228:229]
	v_pk_mul_f32 v[212:213], v[216:217], v[232:233]
	v_lshlrev_b32_e32 v226, 16, v176
	v_and_b32_e32 v227, 0xffff0000, v176
	v_lshlrev_b32_e32 v228, 16, v177
	v_and_b32_e32 v229, 0xffff0000, v177
	v_lshlrev_b32_e32 v230, 16, v188
	v_and_b32_e32 v231, 0xffff0000, v188
	v_lshlrev_b32_e32 v232, 16, v189
	v_and_b32_e32 v233, 0xffff0000, v189
	v_pk_mul_f32 v[214:215], v[8:9], v[226:227]
	v_pk_fma_f32 v[210:211], v[214:215], v[230:231], v[210:211]
	v_pk_mul_f32 v[216:217], v[10:11], v[228:229]
	v_pk_fma_f32 v[212:213], v[216:217], v[232:233], v[212:213]
	v_lshlrev_b32_e32 v226, 16, v178
	v_and_b32_e32 v227, 0xffff0000, v178
	v_lshlrev_b32_e32 v228, 16, v179
	v_and_b32_e32 v229, 0xffff0000, v179
	v_lshlrev_b32_e32 v230, 16, v190
	v_and_b32_e32 v231, 0xffff0000, v190
	v_lshlrev_b32_e32 v232, 16, v191
	v_and_b32_e32 v233, 0xffff0000, v191
	v_pk_mul_f32 v[214:215], v[0:1], v[226:227]
	v_pk_fma_f32 v[210:211], v[214:215], v[230:231], v[210:211]
	v_pk_mul_f32 v[216:217], v[2:3], v[228:229]
	v_pk_fma_f32 v[212:213], v[216:217], v[232:233], v[212:213]
	v_lshlrev_b32_e32 v226, 16, v198
	v_and_b32_e32 v227, 0xffff0000, v198
	v_lshlrev_b32_e32 v228, 16, v199
	v_and_b32_e32 v229, 0xffff0000, v199
	v_pk_mul_f32 v[210:211], v[210:211], v[226:227]
	v_pk_mul_f32 v[212:213], v[212:213], v[228:229]
	v_cvt_pk_bf16_f32 v136, v210, v211
	v_cvt_pk_bf16_f32 v137, v212, v213
	global_store_dwordx2 v114, v[136:137], s[12:13] offset:1536
	s_waitcnt vmcnt(2)
; __device__ __forceinline__ void prep_tokens(const bf16* Y, bf16* MIX, const float* scw, int tb, int te, int wi, int ws_, int lane) {
;     ...
;         { const f32x4 w0 = cw0 * fp, w2 = cw2 * fn;
;           const float o0 = bflo(gb.x) * (w0.x * bflo(c0.x) * bflo(i0.x) + cw1.x * bflo(c1.x) * bflo(i1.x) + w2.x * bflo(c2.x) * bflo(i2.x));
;           const float o1 = bfhi(gb.x) * (w0.y * bfhi(c0.x) * bfhi(i0.x) + cw1.y * bfhi(c1.x) * bfhi(i1.x) + w2.y * bfhi(c2.x) * bfhi(i2.x));
;           const float o2 = bflo(gb.y) * (w0.z * bflo(c0.y) * bflo(i0.y) + cw1.z * bflo(c1.y) * bflo(i1.y) + w2.z * bflo(c2.y) * bflo(i2.y));
;           const float o3 = bfhi(gb.y) * (w0.w * bfhi(c0.y) * bfhi(i0.y) + cw1.w * bfhi(c1.y) * bfhi(i1.y) + w2.w * bfhi(c2.y) * bfhi(i2.y));
;           v2u w; w.x = pk2(o0, o1); w.y = pk2(o2, o3); *(v2u*)(MIX + (size_t)t * DM + 768 + ch) = w; }
	v_lshlrev_b32_e32 v226, 16, v176
	v_and_b32_e32 v227, 0xffff0000, v176
	v_lshlrev_b32_e32 v228, 16, v177
	v_and_b32_e32 v229, 0xffff0000, v177
	v_lshlrev_b32_e32 v230, 16, v188
	v_and_b32_e32 v231, 0xffff0000, v188
	v_lshlrev_b32_e32 v232, 16, v189
	v_and_b32_e32 v233, 0xffff0000, v189
	v_pk_mul_f32 v[222:223], v[4:5], v[226:227]
	v_pk_mul_f32 v[218:219], v[222:223], v[230:231]
	v_pk_mul_f32 v[224:225], v[6:7], v[228:229]
	v_pk_mul_f32 v[220:221], v[224:225], v[232:233]
	v_lshlrev_b32_e32 v226, 16, v178
	v_and_b32_e32 v227, 0xffff0000, v178
	v_lshlrev_b32_e32 v228, 16, v179
	v_and_b32_e32 v229, 0xffff0000, v179
	v_lshlrev_b32_e32 v230, 16, v190
	v_and_b32_e32 v231, 0xffff0000, v190
	v_lshlrev_b32_e32 v232, 16, v191
	v_and_b32_e32 v233, 0xffff0000, v191
	v_pk_mul_f32 v[222:223], v[8:9], v[226:227]
	v_pk_fma_f32 v[218:219], v[222:223], v[230:231], v[218:219]
	v_pk_mul_f32 v[224:225], v[10:11], v[228:229]
	v_pk_fma_f32 v[220:221], v[224:225], v[232:233], v[220:221]
	v_lshlrev_b32_e32 v226, 16, v180
	v_and_b32_e32 v227, 0xffff0000, v180
	v_lshlrev_b32_e32 v228, 16, v181
	v_and_b32_e32 v229, 0xffff0000, v181
	v_lshlrev_b32_e32 v230, 16, v192
	v_and_b32_e32 v231, 0xffff0000, v192
	v_lshlrev_b32_e32 v232, 16, v193
	v_and_b32_e32 v233, 0xffff0000, v193
	v_pk_mul_f32 v[222:223], v[0:1], v[226:227]
	v_pk_fma_f32 v[218:219], v[222:223], v[230:231], v[218:219]
	v_pk_mul_f32 v[224:225], v[2:3], v[228:229]
	v_pk_fma_f32 v[220:221], v[224:225], v[232:233], v[220:221]
	v_lshlrev_b32_e32 v226, 16, v200
	v_and_b32_e32 v227, 0xffff0000, v200
	v_lshlrev_b32_e32 v228, 16, v201
	v_and_b32_e32 v229, 0xffff0000, v201
	v_pk_mul_f32 v[218:219], v[218:219], v[226:227]
	v_pk_mul_f32 v[220:221], v[220:221], v[228:229]
	v_cvt_pk_bf16_f32 v140, v218, v219
	v_cvt_pk_bf16_f32 v141, v220, v221
	global_store_dwordx2 v115, v[140:141], s[12:13] offset:1536
	s_waitcnt vmcnt(1)
	v_lshlrev_b32_e32 v226, 16, v178
	v_and_b32_e32 v227, 0xffff0000, v178
	v_lshlrev_b32_e32 v228, 16, v179
	v_and_b32_e32 v229, 0xffff0000, v179
	v_lshlrev_b32_e32 v230, 16, v190
	v_and_b32_e32 v231, 0xffff0000, v190
	v_lshlrev_b32_e32 v232, 16, v191
	v_and_b32_e32 v233, 0xffff0000, v191
	v_pk_mul_f32 v[214:215], v[4:5], v[226:227]
	v_pk_mul_f32 v[210:211], v[214:215], v[230:231]
	v_pk_mul_f32 v[216:217], v[6:7], v[228:229]
	v_pk_mul_f32 v[212:213], v[216:217], v[232:233]
	v_lshlrev_b32_e32 v226, 16, v180
	v_and_b32_e32 v227, 0xffff0000, v180
	v_lshlrev_b32_e32 v228, 16, v181
	v_and_b32_e32 v229, 0xffff0000, v181
	v_lshlrev_b32_e32 v230, 16, v192
	v_and_b32_e32 v231, 0xffff0000, v192
	v_lshlrev_b32_e32 v232, 16, v193
	v_and_b32_e32 v233, 0xffff0000, v193
	v_pk_mul_f32 v[214:215], v[8:9], v[226:227]
	v_pk_fma_f32 v[210:211], v[214:215], v[230:231], v[210:211]
	v_pk_mul_f32 v[216:217], v[10:11], v[228:229]
	v_pk_fma_f32 v[212:213], v[216:217], v[232:233], v[212:213]
	v_lshlrev_b32_e32 v226, 16, v182
	v_and_b32_e32 v227, 0xffff0000, v182
	v_lshlrev_b32_e32 v228, 16, v183
	v_and_b32_e32 v229, 0xffff0000, v183
	v_lshlrev_b32_e32 v230, 16, v194
	v_and_b32_e32 v231, 0xffff0000, v194
	v_lshlrev_b32_e32 v232, 16, v195
	v_and_b32_e32 v233, 0xffff0000, v195
	v_pk_mul_f32 v[214:215], v[0:1], v[226:227]
	v_pk_fma_f32 v[210:211], v[214:215], v[230:231], v[210:211]
	v_pk_mul_f32 v[216:217], v[2:3], v[228:229]
	v_pk_fma_f32 v[212:213], v[216:217], v[232:233], v[212:213]
	v_lshlrev_b32_e32 v226, 16, v202
	v_and_b32_e32 v227, 0xffff0000, v202
	v_lshlrev_b32_e32 v228, 16, v203
	v_and_b32_e32 v229, 0xffff0000, v203
	v_pk_mul_f32 v[210:211], v[210:211], v[226:227]
	v_pk_mul_f32 v[212:213], v[212:213], v[228:229]
	v_cvt_pk_bf16_f32 v144, v210, v211
	v_cvt_pk_bf16_f32 v145, v212, v213
	global_store_dwordx2 v116, v[144:145], s[12:13] offset:1536
	s_waitcnt vmcnt(0)
	v_lshlrev_b32_e32 v226, 16, v180
	v_and_b32_e32 v227, 0xffff0000, v180
	v_lshlrev_b32_e32 v228, 16, v181
	v_and_b32_e32 v229, 0xffff0000, v181
	v_lshlrev_b32_e32 v230, 16, v192
	v_and_b32_e32 v231, 0xffff0000, v192
	v_lshlrev_b32_e32 v232, 16, v193
	v_and_b32_e32 v233, 0xffff0000, v193
	v_pk_mul_f32 v[222:223], v[4:5], v[226:227]
	v_pk_mul_f32 v[218:219], v[222:223], v[230:231]
	v_pk_mul_f32 v[224:225], v[6:7], v[228:229]
	v_pk_mul_f32 v[220:221], v[224:225], v[232:233]
	v_lshlrev_b32_e32 v226, 16, v182
	v_and_b32_e32 v227, 0xffff0000, v182
	v_lshlrev_b32_e32 v228, 16, v183
	v_and_b32_e32 v229, 0xffff0000, v183
	v_lshlrev_b32_e32 v230, 16, v194
	v_and_b32_e32 v231, 0xffff0000, v194
	v_lshlrev_b32_e32 v232, 16, v195
	v_and_b32_e32 v233, 0xffff0000, v195
	v_pk_mul_f32 v[222:223], v[8:9], v[226:227]
	v_pk_fma_f32 v[218:219], v[222:223], v[230:231], v[218:219]
	v_pk_mul_f32 v[224:225], v[10:11], v[228:229]
	v_pk_fma_f32 v[220:221], v[224:225], v[232:233], v[220:221]
	v_lshlrev_b32_e32 v226, 16, v184
	v_and_b32_e32 v227, 0xffff0000, v184
	v_lshlrev_b32_e32 v228, 16, v185
	v_and_b32_e32 v229, 0xffff0000, v185
	v_lshlrev_b32_e32 v230, 16, v196
	v_and_b32_e32 v231, 0xffff0000, v196
	v_lshlrev_b32_e32 v232, 16, v197
	v_and_b32_e32 v233, 0xffff0000, v197
	v_pk_mul_f32 v[222:223], v[0:1], v[226:227]
	v_pk_fma_f32 v[218:219], v[222:223], v[230:231], v[218:219]
	v_pk_mul_f32 v[224:225], v[2:3], v[228:229]
	v_pk_fma_f32 v[220:221], v[224:225], v[232:233], v[220:221]
	v_lshlrev_b32_e32 v226, 16, v204
	v_and_b32_e32 v227, 0xffff0000, v204
	v_lshlrev_b32_e32 v228, 16, v205
	v_and_b32_e32 v229, 0xffff0000, v205
	v_pk_mul_f32 v[218:219], v[218:219], v[226:227]
	v_pk_mul_f32 v[220:221], v[220:221], v[228:229]
	v_cvt_pk_bf16_f32 v148, v218, v219
	v_cvt_pk_bf16_f32 v149, v220, v221
	global_store_dwordx2 v117, v[148:149], s[12:13] offset:1536
	s_branch .LBB0_588
